# P1+P8 K-loops: B-operand LDS addresses from one loop-invariant base VGPR plus immediates (4 v_add_u32 per iteration removed)
# baseline (speedup 1.0000x reference)
.LBB0_322:
	s_lshl_b32 s15, s14, 5
	s_mov_b64 s[10:11], 0x80
	s_and_b32 s50, s15, 0x60
	s_add_i32 m0, s40, 0x18000
	v_lshl_add_u64 v[8:9], v[8:9], 0, s[10:11]
	s_lshl_b32 s45, s7, 6
	s_lshl_b32 s5, s7, 13
	s_lshl_b32 s20, s50, 7
	s_waitcnt vmcnt(2)
	s_barrier
	global_load_lds_dwordx4 v[8:9], off
	v_lshl_add_u64 v[6:7], v[6:7], 0, s[10:11]
	s_add_i32 m0, s40, 0x1a000
	s_add_i32 s51, s40, 0x8000
	s_add_i32 s52, s40, 0xa000
	global_load_lds_dwordx4 v[6:7], off
	v_lshl_add_u64 v[2:3], v[2:3], 0, s[10:11]
	s_mov_b32 m0, s51
	s_add_u32 s18, s30, 0x40080
	global_load_lds_dwordx4 v[2:3], off
	v_lshl_add_u64 v[2:3], v[4:5], 0, s[10:11]
	s_mov_b32 m0, s52
	s_addc_u32 s19, s31, 0
	global_load_lds_dwordx4 v[2:3], off
	s_add_i32 m0, s40, 0x1c000
	v_lshl_add_u64 v[2:3], s[18:19], 0, v[202:203]
	global_load_lds_dwordx4 v[2:3], off
	v_lshl_add_u64 v[2:3], s[18:19], 0, v[198:199]
	s_add_i32 m0, s40, 0x1e000
	v_lshlrev_b32_e32 v4, 2, v216
	global_load_lds_dwordx4 v[2:3], off
	v_and_b32_e32 v2, 48, v0
	v_lshl_or_b32 v3, v216, 6, v2
	v_or_b32_e32 v2, v217, v2
	v_and_b32_e32 v4, 32, v4
	v_bitop3_b32 v225, s20, v2, v218 bitop3:0xf6
	v_lshlrev_b32_e32 v2, 8, v0
	v_bitop3_b32 v3, v3, s5, v4 bitop3:0xde
	v_and_b32_e32 v2, 0x18000, v2
	v_lshlrev_b32_e32 v4, 11, v12
	v_and_or_b32 v227, v0, 31, s15
	s_lshl_b32 s14, s14, 7
	s_add_i32 s15, 0, 0x21000
	v_or3_b32 v2, v10, v2, v4
	s_add_i32 s14, s15, s14
	v_add_u32_e32 v206, v2, v11
	v_lshlrev_b32_e32 v2, 4, v13
	s_waitcnt vmcnt(6)
	s_cmpk_lt_u32 s6, 0x100
	v_and_b32_e32 v2, 0x38000, v2
	s_cselect_b64 s[18:19], -1, 0
	s_lshl_b32 s6, s7, 8
	v_or3_b32 v2, v10, v2, v4
	s_sext_i32_i16 s2, s4
	v_lshrrev_b32_e32 v224, 4, v252
	v_cmp_gt_u32_e64 s[4:5], 32, v252
	v_lshl_add_u32 v228, v252, 2, s14
	s_add_i32 s14, s15, s6
	s_ashr_i32 s15, s3, 31
	v_mov_b32_e32 v207, v203
	v_add_u32_e32 v208, v2, v11
	v_mov_b32_e32 v209, v203
	v_mov_b64_e32 v[210:211], 0x580
	v_mov_b64_e32 v[212:213], 0x57f
	s_add_i32 s53, 0, 0x10000
	s_add_i32 s54, 0, 0x14000
	v_add_u32_e32 v229, 0, v3
	v_mov_b32_e32 v230, 0x358637bd
	s_movk_i32 s55, 0x1600
	s_barrier
	v_add_u32_e32 v236, 0x10000, v225
	s_branch .LBB0_325

.LBB0_330:
	ds_read_b128 v[134:137], v236
	ds_read_b128 v[138:141], v236 offset:1024
	ds_read_b128 v[142:145], v236 offset:2048
	ds_read_b128 v[146:149], v236 offset:3072
	ds_read_b128 v[150:153], v236 offset:16384
	ds_read_b128 v[154:157], v236 offset:17408
	ds_read_b128 v[158:161], v236 offset:18432
	ds_read_b128 v[162:165], v236 offset:19456
	ds_read_b128 v[166:169], v229
	ds_read_b128 v[170:173], v229 offset:1024
	ds_read_b128 v[174:177], v229 offset:2048
	ds_read_b128 v[178:181], v229 offset:3072
	ds_read_b128 v[182:185], v229 offset:4096
	ds_read_b128 v[186:189], v229 offset:5120
	ds_read_b128 v[190:193], v229 offset:6144
	ds_read_b128 v[194:197], v229 offset:7168
	s_add_i32 s61, s61, 2
	s_cmp_gt_i32 s61, 13
	s_cbranch_scc1 .Lkr1_exit
	s_add_u32 s28, s28, 0x100
	s_addc_u32 s29, s29, 0
	s_add_u32 s59, s59, 0x100
	s_addc_u32 s60, s60, 0
	s_cmp_eq_u32 s61, 12
	s_cselect_b64 s[30:31], -1, 0
	s_cbranch_scc0 .LBB0_332
	global_load_dwordx4 v[2:5], v[214:215], off
.LBB0_332:
	s_add_u32 s48, s28, 0xfffc0080
	s_addc_u32 s49, s29, -1
	s_and_b64 s[46:47], s[30:31], exec
	s_cselect_b32 s49, s23, s49
	s_cselect_b32 s48, s56, s48
	s_cselect_b32 s47, s57, s60
	s_cselect_b32 s46, s58, s59
	s_add_i32 m0, s40, 0xc000
	s_nop 0
	global_load_lds_dwordx4 v206, s[28:29]
	s_add_i32 m0, s40, 0xe000
	s_nop 0
	global_load_lds_dwordx4 v208, s[28:29]
	s_waitcnt vmcnt(8) lgkmcnt(0)
	s_barrier
	v_mfma_f32_16x16x32_bf16 v[130:133], v[134:137], v[166:169], v[130:133]
	v_mfma_f32_16x16x32_bf16 v[122:125], v[142:145], v[166:169], v[122:125]
	v_mfma_f32_16x16x32_bf16 v[114:117], v[134:137], v[174:177], v[114:117]
	v_mfma_f32_16x16x32_bf16 v[106:109], v[142:145], v[174:177], v[106:109]
	v_mfma_f32_16x16x32_bf16 v[98:101], v[134:137], v[182:185], v[98:101]
	v_mfma_f32_16x16x32_bf16 v[90:93], v[142:145], v[182:185], v[90:93]
	v_mfma_f32_16x16x32_bf16 v[82:85], v[134:137], v[190:193], v[82:85]
	v_mfma_f32_16x16x32_bf16 v[74:77], v[142:145], v[190:193], v[74:77]
	v_mfma_f32_16x16x32_bf16 v[130:133], v[138:141], v[170:173], v[130:133]
	v_mfma_f32_16x16x32_bf16 v[122:125], v[146:149], v[170:173], v[122:125]
	v_mfma_f32_16x16x32_bf16 v[114:117], v[138:141], v[178:181], v[114:117]
	v_mfma_f32_16x16x32_bf16 v[106:109], v[146:149], v[178:181], v[106:109]
	v_mfma_f32_16x16x32_bf16 v[98:101], v[138:141], v[186:189], v[98:101]
	v_mfma_f32_16x16x32_bf16 v[90:93], v[146:149], v[186:189], v[90:93]
	v_mfma_f32_16x16x32_bf16 v[82:85], v[138:141], v[194:197], v[82:85]
	v_mfma_f32_16x16x32_bf16 v[74:77], v[146:149], v[194:197], v[74:77]
	v_mfma_f32_16x16x32_bf16 v[126:129], v[150:153], v[166:169], v[126:129]
	v_mfma_f32_16x16x32_bf16 v[118:121], v[158:161], v[166:169], v[118:121]
	v_mfma_f32_16x16x32_bf16 v[110:113], v[150:153], v[174:177], v[110:113]
	v_mfma_f32_16x16x32_bf16 v[102:105], v[158:161], v[174:177], v[102:105]
	v_mfma_f32_16x16x32_bf16 v[94:97], v[150:153], v[182:185], v[94:97]
	v_mfma_f32_16x16x32_bf16 v[86:89], v[158:161], v[182:185], v[86:89]
	v_mfma_f32_16x16x32_bf16 v[78:81], v[150:153], v[190:193], v[78:81]
	v_mfma_f32_16x16x32_bf16 v[70:73], v[158:161], v[190:193], v[70:73]
	v_mfma_f32_16x16x32_bf16 v[126:129], v[154:157], v[170:173], v[126:129]
	v_mfma_f32_16x16x32_bf16 v[118:121], v[162:165], v[170:173], v[118:121]
	v_mfma_f32_16x16x32_bf16 v[110:113], v[154:157], v[178:181], v[110:113]
	v_mfma_f32_16x16x32_bf16 v[102:105], v[162:165], v[178:181], v[102:105]
	v_mfma_f32_16x16x32_bf16 v[94:97], v[154:157], v[186:189], v[94:97]
	v_mfma_f32_16x16x32_bf16 v[86:89], v[162:165], v[186:189], v[86:89]
	v_mfma_f32_16x16x32_bf16 v[78:81], v[154:157], v[194:197], v[78:81]
	v_mfma_f32_16x16x32_bf16 v[70:73], v[162:165], v[194:197], v[70:73]
	s_barrier
	ds_read_b128 v[166:169], v229 offset:16384
	ds_read_b128 v[170:173], v229 offset:17408
	ds_read_b128 v[174:177], v229 offset:18432
	ds_read_b128 v[178:181], v229 offset:19456
	ds_read_b128 v[182:185], v229 offset:20480
	ds_read_b128 v[186:189], v229 offset:21504
	ds_read_b128 v[190:193], v229 offset:22528
	ds_read_b128 v[194:197], v229 offset:23552
	s_add_i32 s62, s53, s12
	s_add_u32 s98, s46, s10
	s_addc_u32 s99, s47, s11
	s_mov_b32 m0, s62
	s_nop 0
	global_load_lds_dwordx4 v202, s[46:47]
	s_add_i32 m0, s62, 0x2000
	s_add_u32 s62, s46, 0x40000
	s_addc_u32 s63, s47, 0
	s_add_i32 s64, s54, s12
	global_load_lds_dwordx4 v198, s[46:47]
	s_mov_b32 m0, s64
	s_add_u32 s100, s48, s10
	s_addc_u32 s101, s49, s11
	global_load_lds_dwordx4 v202, s[62:63]
	s_add_i32 m0, s64, 0x2000
	s_nop 0
	global_load_lds_dwordx4 v198, s[62:63]
	s_mov_b32 m0, s40
	s_nop 0
	global_load_lds_dwordx4 v204, s[48:49]
	s_mov_b32 m0, s41
	s_nop 0
	global_load_lds_dwordx4 v200, s[48:49]
	s_waitcnt vmcnt(8) lgkmcnt(0)
	s_barrier
	v_mfma_f32_16x16x32_bf16 v[66:69], v[134:137], v[166:169], v[66:69]
	v_mfma_f32_16x16x32_bf16 v[58:61], v[142:145], v[166:169], v[58:61]
	v_mfma_f32_16x16x32_bf16 v[50:53], v[134:137], v[174:177], v[50:53]
	v_mfma_f32_16x16x32_bf16 v[42:45], v[142:145], v[174:177], v[42:45]
	v_mfma_f32_16x16x32_bf16 v[34:37], v[134:137], v[182:185], v[34:37]
	v_mfma_f32_16x16x32_bf16 v[26:29], v[142:145], v[182:185], v[26:29]
	v_mfma_f32_16x16x32_bf16 v[18:21], v[134:137], v[190:193], v[18:21]
	v_mfma_f32_16x16x32_bf16 v[10:13], v[142:145], v[190:193], v[10:13]
	v_mfma_f32_16x16x32_bf16 v[66:69], v[138:141], v[170:173], v[66:69]
	v_mfma_f32_16x16x32_bf16 v[58:61], v[146:149], v[170:173], v[58:61]
	v_mfma_f32_16x16x32_bf16 v[50:53], v[138:141], v[178:181], v[50:53]
	v_mfma_f32_16x16x32_bf16 v[42:45], v[146:149], v[178:181], v[42:45]
	v_mfma_f32_16x16x32_bf16 v[34:37], v[138:141], v[186:189], v[34:37]
	v_mfma_f32_16x16x32_bf16 v[26:29], v[146:149], v[186:189], v[26:29]
	v_mfma_f32_16x16x32_bf16 v[18:21], v[138:141], v[194:197], v[18:21]
	v_mfma_f32_16x16x32_bf16 v[10:13], v[146:149], v[194:197], v[10:13]
	v_mfma_f32_16x16x32_bf16 v[62:65], v[150:153], v[166:169], v[62:65]
	v_mfma_f32_16x16x32_bf16 v[54:57], v[158:161], v[166:169], v[54:57]
	v_mfma_f32_16x16x32_bf16 v[46:49], v[150:153], v[174:177], v[46:49]
	v_mfma_f32_16x16x32_bf16 v[38:41], v[158:161], v[174:177], v[38:41]
	v_mfma_f32_16x16x32_bf16 v[30:33], v[150:153], v[182:185], v[30:33]
	v_mfma_f32_16x16x32_bf16 v[22:25], v[158:161], v[182:185], v[22:25]
	v_mfma_f32_16x16x32_bf16 v[14:17], v[150:153], v[190:193], v[14:17]
	v_mfma_f32_16x16x32_bf16 v[6:9], v[158:161], v[190:193], v[6:9]
	v_mfma_f32_16x16x32_bf16 v[62:65], v[154:157], v[170:173], v[62:65]
	v_mfma_f32_16x16x32_bf16 v[54:57], v[162:165], v[170:173], v[54:57]
	v_mfma_f32_16x16x32_bf16 v[46:49], v[154:157], v[178:181], v[46:49]
	v_mfma_f32_16x16x32_bf16 v[38:41], v[162:165], v[178:181], v[38:41]
	v_mfma_f32_16x16x32_bf16 v[30:33], v[154:157], v[186:189], v[30:33]
	v_mfma_f32_16x16x32_bf16 v[22:25], v[162:165], v[186:189], v[22:25]
	v_mfma_f32_16x16x32_bf16 v[14:17], v[154:157], v[194:197], v[14:17]
	v_mfma_f32_16x16x32_bf16 v[6:9], v[162:165], v[194:197], v[6:9]
	s_barrier
	ds_read_b128 v[166:169], v229 offset:32768
	ds_read_b128 v[170:173], v229 offset:33792
	ds_read_b128 v[174:177], v229 offset:34816
	ds_read_b128 v[178:181], v229 offset:35840
	ds_read_b128 v[182:185], v229 offset:36864
	ds_read_b128 v[186:189], v229 offset:37888
	ds_read_b128 v[190:193], v229 offset:38912
	ds_read_b128 v[194:197], v229 offset:39936
	ds_read_b128 v[150:153], v236 offset:32768
	ds_read_b128 v[154:157], v236 offset:33792
	ds_read_b128 v[158:161], v236 offset:34816
	ds_read_b128 v[162:165], v236 offset:35840
	ds_read_b128 v[134:137], v236 offset:49152
	ds_read_b128 v[138:141], v236 offset:50176
	ds_read_b128 v[142:145], v236 offset:51200
	ds_read_b128 v[146:149], v236 offset:52224
	s_add_i32 s62, 0, 0x18000
	s_add_i32 s63, 0, 0x1c000
	s_add_u32 s48, s48, 0x40000
	s_addc_u32 s49, s49, 0
	s_mov_b32 m0, s42
	s_nop 0
	global_load_lds_dwordx4 v204, s[48:49]
	s_mov_b32 m0, s43
	s_nop 0
	global_load_lds_dwordx4 v200, s[48:49]
	s_waitcnt vmcnt(8) lgkmcnt(0)
	s_barrier
	v_mfma_f32_16x16x32_bf16 v[130:133], v[150:153], v[166:169], v[130:133]
	v_mfma_f32_16x16x32_bf16 v[122:125], v[158:161], v[166:169], v[122:125]
	v_mfma_f32_16x16x32_bf16 v[114:117], v[150:153], v[174:177], v[114:117]
	v_mfma_f32_16x16x32_bf16 v[106:109], v[158:161], v[174:177], v[106:109]
	v_mfma_f32_16x16x32_bf16 v[98:101], v[150:153], v[182:185], v[98:101]
	v_mfma_f32_16x16x32_bf16 v[90:93], v[158:161], v[182:185], v[90:93]
	v_mfma_f32_16x16x32_bf16 v[82:85], v[150:153], v[190:193], v[82:85]
	v_mfma_f32_16x16x32_bf16 v[74:77], v[158:161], v[190:193], v[74:77]
	v_mfma_f32_16x16x32_bf16 v[130:133], v[154:157], v[170:173], v[130:133]
	v_mfma_f32_16x16x32_bf16 v[122:125], v[162:165], v[170:173], v[122:125]
	v_mfma_f32_16x16x32_bf16 v[114:117], v[154:157], v[178:181], v[114:117]
	v_mfma_f32_16x16x32_bf16 v[106:109], v[162:165], v[178:181], v[106:109]
	v_mfma_f32_16x16x32_bf16 v[98:101], v[154:157], v[186:189], v[98:101]
	v_mfma_f32_16x16x32_bf16 v[90:93], v[162:165], v[186:189], v[90:93]
	v_mfma_f32_16x16x32_bf16 v[82:85], v[154:157], v[194:197], v[82:85]
	v_mfma_f32_16x16x32_bf16 v[74:77], v[162:165], v[194:197], v[74:77]
	v_mfma_f32_16x16x32_bf16 v[126:129], v[134:137], v[166:169], v[126:129]
	v_mfma_f32_16x16x32_bf16 v[118:121], v[142:145], v[166:169], v[118:121]
	v_mfma_f32_16x16x32_bf16 v[110:113], v[134:137], v[174:177], v[110:113]
	v_mfma_f32_16x16x32_bf16 v[102:105], v[142:145], v[174:177], v[102:105]
	v_mfma_f32_16x16x32_bf16 v[94:97], v[134:137], v[182:185], v[94:97]
	v_mfma_f32_16x16x32_bf16 v[86:89], v[142:145], v[182:185], v[86:89]
	v_mfma_f32_16x16x32_bf16 v[78:81], v[134:137], v[190:193], v[78:81]
	v_mfma_f32_16x16x32_bf16 v[70:73], v[142:145], v[190:193], v[70:73]
	v_mfma_f32_16x16x32_bf16 v[126:129], v[138:141], v[170:173], v[126:129]
	v_mfma_f32_16x16x32_bf16 v[118:121], v[146:149], v[170:173], v[118:121]
	v_mfma_f32_16x16x32_bf16 v[110:113], v[138:141], v[178:181], v[110:113]
	v_mfma_f32_16x16x32_bf16 v[102:105], v[146:149], v[178:181], v[102:105]
	v_mfma_f32_16x16x32_bf16 v[94:97], v[138:141], v[186:189], v[94:97]
	v_mfma_f32_16x16x32_bf16 v[86:89], v[146:149], v[186:189], v[86:89]
	v_mfma_f32_16x16x32_bf16 v[78:81], v[138:141], v[194:197], v[78:81]
	v_mfma_f32_16x16x32_bf16 v[70:73], v[146:149], v[194:197], v[70:73]
	s_barrier
	ds_read_b128 v[190:193], v229 offset:49152
	ds_read_b128 v[194:197], v229 offset:50176
	ds_read_b128 v[182:185], v229 offset:51200
	ds_read_b128 v[186:189], v229 offset:52224
	ds_read_b128 v[174:177], v229 offset:53248
	ds_read_b128 v[178:181], v229 offset:54272
	ds_read_b128 v[166:169], v229 offset:55296
	ds_read_b128 v[170:173], v229 offset:56320
	s_add_i32 s48, s62, s12
	s_mov_b32 m0, s48
	s_nop 0
	global_load_lds_dwordx4 v202, s[98:99]
	s_add_i32 m0, s48, 0x2000
	s_add_u32 s46, s46, 0x40080
	s_addc_u32 s47, s47, 0
	s_add_i32 s48, s63, s12
	global_load_lds_dwordx4 v198, s[98:99]
	s_mov_b32 m0, s48
	s_andn2_b64 vcc, exec, s[30:31]
	global_load_lds_dwordx4 v202, s[46:47]
	s_add_i32 m0, s48, 0x2000
	s_nop 0
	global_load_lds_dwordx4 v198, s[46:47]
	s_mov_b32 m0, s51
	s_nop 0
	global_load_lds_dwordx4 v204, s[100:101]
	s_mov_b32 m0, s52
	s_nop 0
	global_load_lds_dwordx4 v200, s[100:101]
	s_waitcnt vmcnt(8)
	s_cbranch_vccnz .LBB0_329
	s_and_saveexec_b64 s[30:31], s[4:5]
	s_cbranch_execz .LBB0_328
	v_mov_b32_e32 v232, v3
	v_mov_b32_e32 v233, v4
	v_mov_b32_e32 v234, v2
	v_mov_b32_e32 v235, v5
	v_pk_add_f32 v[232:233], v[232:233], v[234:235]
	s_nop 0
	v_add_f32_e32 v226, v232, v233
	v_fmamk_f32 v226, v226, 0x3a800000, v230
	ds_write_b32 v228, v226
	s_branch .LBB0_328

.LBB0_1758:
	s_lshl_b32 s15, s14, 5
	s_mov_b64 s[16:17], 0x80
	s_and_b32 s50, s15, 0x60
	s_add_i32 m0, s40, 0x18000
	v_lshl_add_u64 v[8:9], v[8:9], 0, s[16:17]
	s_lshl_b32 s45, s7, 6
	s_lshl_b32 s5, s7, 13
	s_lshl_b32 s20, s50, 7
	s_waitcnt vmcnt(2)
	s_barrier
	global_load_lds_dwordx4 v[8:9], off
	v_lshl_add_u64 v[6:7], v[6:7], 0, s[16:17]
	s_add_i32 m0, s40, 0x1a000
	s_add_i32 s51, s40, 0x8000
	s_add_i32 s52, s40, 0xa000
	global_load_lds_dwordx4 v[6:7], off
	v_lshl_add_u64 v[2:3], v[2:3], 0, s[16:17]
	s_mov_b32 m0, s51
	s_add_u32 s18, s30, 0x40080
	global_load_lds_dwordx4 v[2:3], off
	v_lshl_add_u64 v[2:3], v[4:5], 0, s[16:17]
	s_mov_b32 m0, s52
	s_addc_u32 s19, s31, 0
	global_load_lds_dwordx4 v[2:3], off
	s_add_i32 m0, s40, 0x1c000
	v_lshl_add_u64 v[2:3], s[18:19], 0, v[202:203]
	global_load_lds_dwordx4 v[2:3], off
	v_lshl_add_u64 v[2:3], s[18:19], 0, v[198:199]
	s_add_i32 m0, s40, 0x1e000
	s_sext_i32_i16 s2, s4
	global_load_lds_dwordx4 v[2:3], off
	v_and_b32_e32 v1, 15, v0
	v_and_b32_e32 v2, 48, v0
	v_lshlrev_b32_e32 v4, 2, v0
	v_lshlrev_b32_e32 v5, 6, v0
	s_movk_i32 s4, 0x3c0
	v_lshl_or_b32 v3, v1, 6, v2
	v_and_b32_e32 v4, 32, v4
	v_and_or_b32 v2, v5, s4, v2
	v_bitop3_b32 v217, s20, v2, v4 bitop3:0xf6
	v_lshlrev_b32_e32 v2, 8, v0
	v_bitop3_b32 v3, v3, s5, v4 bitop3:0xde
	v_and_b32_e32 v2, 0x18000, v2
	v_lshlrev_b32_e32 v4, 11, v13
	v_and_or_b32 v218, v0, 31, s15
	s_lshl_b32 s14, s14, 7
	s_add_i32 s15, 0, 0x21000
	v_or3_b32 v2, v11, v2, v4
	s_add_i32 s14, s15, s14
	v_add_u32_e32 v206, v2, v12
	v_lshlrev_b32_e32 v2, 4, v10
	s_waitcnt vmcnt(6)
	s_cmpk_lt_u32 s6, 0x100
	v_and_b32_e32 v2, 0x38000, v2
	s_cselect_b64 s[18:19], -1, 0
	s_lshl_b32 s6, s7, 8
	v_or3_b32 v2, v11, v2, v4
	v_lshrrev_b32_e32 v216, 4, v252
	v_cmp_gt_u32_e64 s[4:5], 32, v252
	v_lshl_add_u32 v219, v252, 2, s14
	s_add_i32 s14, s15, s6
	s_ashr_i32 s15, s3, 31
	v_mov_b32_e32 v207, v203
	v_add_u32_e32 v208, v2, v12
	v_mov_b32_e32 v209, v203
	v_mov_b64_e32 v[210:211], 0x580
	v_mov_b64_e32 v[212:213], 0x57f
	s_add_i32 s53, 0, 0x10000
	s_add_i32 s54, 0, 0x14000
	v_add_u32_e32 v220, 0, v3
	v_mov_b32_e32 v221, 0x358637bd
	s_movk_i32 s55, 0x1600
	s_barrier
	v_add_u32_e32 v226, 0x10000, v217
	s_branch .LBB0_1761

.LBB0_1766:
	ds_read_b128 v[134:137], v226
	ds_read_b128 v[138:141], v226 offset:1024
	ds_read_b128 v[142:145], v226 offset:2048
	ds_read_b128 v[146:149], v226 offset:3072
	ds_read_b128 v[150:153], v226 offset:16384
	ds_read_b128 v[154:157], v226 offset:17408
	ds_read_b128 v[158:161], v226 offset:18432
	ds_read_b128 v[162:165], v226 offset:19456
	ds_read_b128 v[166:169], v220
	ds_read_b128 v[170:173], v220 offset:1024
	ds_read_b128 v[174:177], v220 offset:2048
	ds_read_b128 v[178:181], v220 offset:3072
	ds_read_b128 v[182:185], v220 offset:4096
	ds_read_b128 v[186:189], v220 offset:5120
	ds_read_b128 v[190:193], v220 offset:6144
	ds_read_b128 v[194:197], v220 offset:7168
	s_add_i32 s61, s61, 2
	s_cmp_gt_i32 s61, 13
	s_cbranch_scc1 .Lkr8_exit
	s_add_u32 s28, s28, 0x100
	s_addc_u32 s29, s29, 0
	s_add_u32 s59, s59, 0x100
	s_addc_u32 s60, s60, 0
	s_cmp_eq_u32 s61, 12
	s_cselect_b64 s[30:31], -1, 0
	s_cbranch_scc0 .LBB0_1768
	global_load_dwordx4 v[2:5], v[214:215], off
.LBB0_1768:
	s_add_u32 s48, s28, 0xfffc0080
	s_addc_u32 s49, s29, -1
	s_and_b64 s[46:47], s[30:31], exec
	s_cselect_b32 s49, s23, s49
	s_cselect_b32 s48, s56, s48
	s_cselect_b32 s47, s57, s60
	s_cselect_b32 s46, s58, s59
	s_add_i32 m0, s40, 0xc000
	s_nop 0
	global_load_lds_dwordx4 v206, s[28:29]
	s_add_i32 m0, s40, 0xe000
	s_nop 0
	global_load_lds_dwordx4 v208, s[28:29]
	s_waitcnt vmcnt(8) lgkmcnt(0)
	s_barrier
	v_mfma_f32_16x16x32_bf16 v[130:133], v[134:137], v[166:169], v[130:133]
	v_mfma_f32_16x16x32_bf16 v[122:125], v[142:145], v[166:169], v[122:125]
	v_mfma_f32_16x16x32_bf16 v[114:117], v[134:137], v[174:177], v[114:117]
	v_mfma_f32_16x16x32_bf16 v[106:109], v[142:145], v[174:177], v[106:109]
	v_mfma_f32_16x16x32_bf16 v[98:101], v[134:137], v[182:185], v[98:101]
	v_mfma_f32_16x16x32_bf16 v[90:93], v[142:145], v[182:185], v[90:93]
	v_mfma_f32_16x16x32_bf16 v[82:85], v[134:137], v[190:193], v[82:85]
	v_mfma_f32_16x16x32_bf16 v[74:77], v[142:145], v[190:193], v[74:77]
	v_mfma_f32_16x16x32_bf16 v[130:133], v[138:141], v[170:173], v[130:133]
	v_mfma_f32_16x16x32_bf16 v[122:125], v[146:149], v[170:173], v[122:125]
	v_mfma_f32_16x16x32_bf16 v[114:117], v[138:141], v[178:181], v[114:117]
	v_mfma_f32_16x16x32_bf16 v[106:109], v[146:149], v[178:181], v[106:109]
	v_mfma_f32_16x16x32_bf16 v[98:101], v[138:141], v[186:189], v[98:101]
	v_mfma_f32_16x16x32_bf16 v[90:93], v[146:149], v[186:189], v[90:93]
	v_mfma_f32_16x16x32_bf16 v[82:85], v[138:141], v[194:197], v[82:85]
	v_mfma_f32_16x16x32_bf16 v[74:77], v[146:149], v[194:197], v[74:77]
	v_mfma_f32_16x16x32_bf16 v[126:129], v[150:153], v[166:169], v[126:129]
	v_mfma_f32_16x16x32_bf16 v[118:121], v[158:161], v[166:169], v[118:121]
	v_mfma_f32_16x16x32_bf16 v[110:113], v[150:153], v[174:177], v[110:113]
	v_mfma_f32_16x16x32_bf16 v[102:105], v[158:161], v[174:177], v[102:105]
	v_mfma_f32_16x16x32_bf16 v[94:97], v[150:153], v[182:185], v[94:97]
	v_mfma_f32_16x16x32_bf16 v[86:89], v[158:161], v[182:185], v[86:89]
	v_mfma_f32_16x16x32_bf16 v[78:81], v[150:153], v[190:193], v[78:81]
	v_mfma_f32_16x16x32_bf16 v[70:73], v[158:161], v[190:193], v[70:73]
	v_mfma_f32_16x16x32_bf16 v[126:129], v[154:157], v[170:173], v[126:129]
	v_mfma_f32_16x16x32_bf16 v[118:121], v[162:165], v[170:173], v[118:121]
	v_mfma_f32_16x16x32_bf16 v[110:113], v[154:157], v[178:181], v[110:113]
	v_mfma_f32_16x16x32_bf16 v[102:105], v[162:165], v[178:181], v[102:105]
	v_mfma_f32_16x16x32_bf16 v[94:97], v[154:157], v[186:189], v[94:97]
	v_mfma_f32_16x16x32_bf16 v[86:89], v[162:165], v[186:189], v[86:89]
	v_mfma_f32_16x16x32_bf16 v[78:81], v[154:157], v[194:197], v[78:81]
	v_mfma_f32_16x16x32_bf16 v[70:73], v[162:165], v[194:197], v[70:73]
	s_barrier
	ds_read_b128 v[166:169], v220 offset:16384
	ds_read_b128 v[170:173], v220 offset:17408
	ds_read_b128 v[174:177], v220 offset:18432
	ds_read_b128 v[178:181], v220 offset:19456
	ds_read_b128 v[182:185], v220 offset:20480
	ds_read_b128 v[186:189], v220 offset:21504
	ds_read_b128 v[190:193], v220 offset:22528
	ds_read_b128 v[194:197], v220 offset:23552
	s_add_i32 s62, s53, s12
	s_add_u32 s98, s46, s16
	s_addc_u32 s99, s47, s17
	s_mov_b32 m0, s62
	s_nop 0
	global_load_lds_dwordx4 v202, s[46:47]
	s_add_i32 m0, s62, 0x2000
	s_add_u32 s62, s46, 0x40000
	s_addc_u32 s63, s47, 0
	s_add_i32 s64, s54, s12
	global_load_lds_dwordx4 v198, s[46:47]
	s_mov_b32 m0, s64
	s_nop 0
	global_load_lds_dwordx4 v202, s[62:63]
	s_add_i32 m0, s64, 0x2000
	s_nop 0
	global_load_lds_dwordx4 v198, s[62:63]
	s_add_u32 s100, s48, s16
	s_addc_u32 s101, s49, s17
	s_mov_b32 m0, s40
	s_nop 0
	global_load_lds_dwordx4 v204, s[48:49]
	s_mov_b32 m0, s41
	s_nop 0
	global_load_lds_dwordx4 v200, s[48:49]
	s_waitcnt vmcnt(8) lgkmcnt(0)
	s_barrier
	v_mfma_f32_16x16x32_bf16 v[66:69], v[134:137], v[166:169], v[66:69]
	v_mfma_f32_16x16x32_bf16 v[58:61], v[142:145], v[166:169], v[58:61]
	v_mfma_f32_16x16x32_bf16 v[50:53], v[134:137], v[174:177], v[50:53]
	v_mfma_f32_16x16x32_bf16 v[42:45], v[142:145], v[174:177], v[42:45]
	v_mfma_f32_16x16x32_bf16 v[34:37], v[134:137], v[182:185], v[34:37]
	v_mfma_f32_16x16x32_bf16 v[26:29], v[142:145], v[182:185], v[26:29]
	v_mfma_f32_16x16x32_bf16 v[18:21], v[134:137], v[190:193], v[18:21]
	v_mfma_f32_16x16x32_bf16 v[10:13], v[142:145], v[190:193], v[10:13]
	v_mfma_f32_16x16x32_bf16 v[66:69], v[138:141], v[170:173], v[66:69]
	v_mfma_f32_16x16x32_bf16 v[58:61], v[146:149], v[170:173], v[58:61]
	v_mfma_f32_16x16x32_bf16 v[50:53], v[138:141], v[178:181], v[50:53]
	v_mfma_f32_16x16x32_bf16 v[42:45], v[146:149], v[178:181], v[42:45]
	v_mfma_f32_16x16x32_bf16 v[34:37], v[138:141], v[186:189], v[34:37]
	v_mfma_f32_16x16x32_bf16 v[26:29], v[146:149], v[186:189], v[26:29]
	v_mfma_f32_16x16x32_bf16 v[18:21], v[138:141], v[194:197], v[18:21]
	v_mfma_f32_16x16x32_bf16 v[10:13], v[146:149], v[194:197], v[10:13]
	v_mfma_f32_16x16x32_bf16 v[62:65], v[150:153], v[166:169], v[62:65]
	v_mfma_f32_16x16x32_bf16 v[54:57], v[158:161], v[166:169], v[54:57]
	v_mfma_f32_16x16x32_bf16 v[46:49], v[150:153], v[174:177], v[46:49]
	v_mfma_f32_16x16x32_bf16 v[38:41], v[158:161], v[174:177], v[38:41]
	v_mfma_f32_16x16x32_bf16 v[30:33], v[150:153], v[182:185], v[30:33]
	v_mfma_f32_16x16x32_bf16 v[22:25], v[158:161], v[182:185], v[22:25]
	v_mfma_f32_16x16x32_bf16 v[14:17], v[150:153], v[190:193], v[14:17]
	v_mfma_f32_16x16x32_bf16 v[6:9], v[158:161], v[190:193], v[6:9]
	v_mfma_f32_16x16x32_bf16 v[62:65], v[154:157], v[170:173], v[62:65]
	v_mfma_f32_16x16x32_bf16 v[54:57], v[162:165], v[170:173], v[54:57]
	v_mfma_f32_16x16x32_bf16 v[46:49], v[154:157], v[178:181], v[46:49]
	v_mfma_f32_16x16x32_bf16 v[38:41], v[162:165], v[178:181], v[38:41]
	v_mfma_f32_16x16x32_bf16 v[30:33], v[154:157], v[186:189], v[30:33]
	v_mfma_f32_16x16x32_bf16 v[22:25], v[162:165], v[186:189], v[22:25]
	v_mfma_f32_16x16x32_bf16 v[14:17], v[154:157], v[194:197], v[14:17]
	v_mfma_f32_16x16x32_bf16 v[6:9], v[162:165], v[194:197], v[6:9]
	s_barrier
	ds_read_b128 v[166:169], v220 offset:32768
	ds_read_b128 v[170:173], v220 offset:33792
	ds_read_b128 v[174:177], v220 offset:34816
	ds_read_b128 v[178:181], v220 offset:35840
	ds_read_b128 v[182:185], v220 offset:36864
	ds_read_b128 v[186:189], v220 offset:37888
	ds_read_b128 v[190:193], v220 offset:38912
	ds_read_b128 v[194:197], v220 offset:39936
	ds_read_b128 v[150:153], v226 offset:32768
	ds_read_b128 v[154:157], v226 offset:33792
	ds_read_b128 v[158:161], v226 offset:34816
	ds_read_b128 v[162:165], v226 offset:35840
	ds_read_b128 v[134:137], v226 offset:49152
	ds_read_b128 v[138:141], v226 offset:50176
	ds_read_b128 v[142:145], v226 offset:51200
	ds_read_b128 v[146:149], v226 offset:52224
	s_add_i32 s62, 0, 0x18000
	s_add_i32 s63, 0, 0x1c000
	s_add_u32 s48, s48, 0x40000
	s_addc_u32 s49, s49, 0
	s_mov_b32 m0, s42
	s_nop 0
	global_load_lds_dwordx4 v204, s[48:49]
	s_mov_b32 m0, s43
	s_nop 0
	global_load_lds_dwordx4 v200, s[48:49]
	s_waitcnt vmcnt(8) lgkmcnt(0)
	s_barrier
	v_mfma_f32_16x16x32_bf16 v[130:133], v[150:153], v[166:169], v[130:133]
	v_mfma_f32_16x16x32_bf16 v[122:125], v[158:161], v[166:169], v[122:125]
	v_mfma_f32_16x16x32_bf16 v[114:117], v[150:153], v[174:177], v[114:117]
	v_mfma_f32_16x16x32_bf16 v[106:109], v[158:161], v[174:177], v[106:109]
	v_mfma_f32_16x16x32_bf16 v[98:101], v[150:153], v[182:185], v[98:101]
	v_mfma_f32_16x16x32_bf16 v[90:93], v[158:161], v[182:185], v[90:93]
	v_mfma_f32_16x16x32_bf16 v[82:85], v[150:153], v[190:193], v[82:85]
	v_mfma_f32_16x16x32_bf16 v[74:77], v[158:161], v[190:193], v[74:77]
	v_mfma_f32_16x16x32_bf16 v[130:133], v[154:157], v[170:173], v[130:133]
	v_mfma_f32_16x16x32_bf16 v[122:125], v[162:165], v[170:173], v[122:125]
	v_mfma_f32_16x16x32_bf16 v[114:117], v[154:157], v[178:181], v[114:117]
	v_mfma_f32_16x16x32_bf16 v[106:109], v[162:165], v[178:181], v[106:109]
	v_mfma_f32_16x16x32_bf16 v[98:101], v[154:157], v[186:189], v[98:101]
	v_mfma_f32_16x16x32_bf16 v[90:93], v[162:165], v[186:189], v[90:93]
	v_mfma_f32_16x16x32_bf16 v[82:85], v[154:157], v[194:197], v[82:85]
	v_mfma_f32_16x16x32_bf16 v[74:77], v[162:165], v[194:197], v[74:77]
	v_mfma_f32_16x16x32_bf16 v[126:129], v[134:137], v[166:169], v[126:129]
	v_mfma_f32_16x16x32_bf16 v[118:121], v[142:145], v[166:169], v[118:121]
	v_mfma_f32_16x16x32_bf16 v[110:113], v[134:137], v[174:177], v[110:113]
	v_mfma_f32_16x16x32_bf16 v[102:105], v[142:145], v[174:177], v[102:105]
	v_mfma_f32_16x16x32_bf16 v[94:97], v[134:137], v[182:185], v[94:97]
	v_mfma_f32_16x16x32_bf16 v[86:89], v[142:145], v[182:185], v[86:89]
	v_mfma_f32_16x16x32_bf16 v[78:81], v[134:137], v[190:193], v[78:81]
	v_mfma_f32_16x16x32_bf16 v[70:73], v[142:145], v[190:193], v[70:73]
	v_mfma_f32_16x16x32_bf16 v[126:129], v[138:141], v[170:173], v[126:129]
	v_mfma_f32_16x16x32_bf16 v[118:121], v[146:149], v[170:173], v[118:121]
	v_mfma_f32_16x16x32_bf16 v[110:113], v[138:141], v[178:181], v[110:113]
	v_mfma_f32_16x16x32_bf16 v[102:105], v[146:149], v[178:181], v[102:105]
	v_mfma_f32_16x16x32_bf16 v[94:97], v[138:141], v[186:189], v[94:97]
	v_mfma_f32_16x16x32_bf16 v[86:89], v[146:149], v[186:189], v[86:89]
	v_mfma_f32_16x16x32_bf16 v[78:81], v[138:141], v[194:197], v[78:81]
	v_mfma_f32_16x16x32_bf16 v[70:73], v[146:149], v[194:197], v[70:73]
	s_barrier
	ds_read_b128 v[190:193], v220 offset:49152
	ds_read_b128 v[194:197], v220 offset:50176
	ds_read_b128 v[182:185], v220 offset:51200
	ds_read_b128 v[186:189], v220 offset:52224
	ds_read_b128 v[174:177], v220 offset:53248
	ds_read_b128 v[178:181], v220 offset:54272
	ds_read_b128 v[166:169], v220 offset:55296
	ds_read_b128 v[170:173], v220 offset:56320
	s_add_i32 s48, s62, s12
	s_mov_b32 m0, s48
	s_nop 0
	global_load_lds_dwordx4 v202, s[98:99]
	s_add_i32 m0, s48, 0x2000
	s_add_u32 s46, s46, 0x40080
	s_addc_u32 s47, s47, 0
	s_add_i32 s48, s63, s12
	global_load_lds_dwordx4 v198, s[98:99]
	s_mov_b32 m0, s48
	s_andn2_b64 vcc, exec, s[30:31]
	global_load_lds_dwordx4 v202, s[46:47]
	s_add_i32 m0, s48, 0x2000
	s_nop 0
	global_load_lds_dwordx4 v198, s[46:47]
	s_mov_b32 m0, s51
	s_nop 0
	global_load_lds_dwordx4 v204, s[100:101]
	s_mov_b32 m0, s52
	s_nop 0
	global_load_lds_dwordx4 v200, s[100:101]
	s_waitcnt vmcnt(8)
	s_cbranch_vccnz .LBB0_1765
	s_and_saveexec_b64 s[30:31], s[4:5]
	s_cbranch_execz .LBB0_1764
	v_mov_b32_e32 v222, v3
	v_mov_b32_e32 v223, v4
	v_mov_b32_e32 v224, v2
	v_mov_b32_e32 v225, v5
	v_pk_add_f32 v[222:223], v[222:223], v[224:225]
	s_nop 0
	v_add_f32_e32 v222, v222, v223
	v_fmamk_f32 v222, v222, 0x3a800000, v221
	ds_write_b32 v219, v222
	s_branch .LBB0_1764
